# layer-1 weight-prep items rebalanced between the idle-tail slots of the first two layer-0 GEMM phases (slot 0 was overloaded by the adaLN items)
# speedup vs baseline: 1.0006x; 1.0001x over previous
.LBB0_300:
	s_or_b64 exec, exec, s[0:1]
	s_sub_i32 s0, s35, s15
	s_lshl_b32 s0, s0, 3
	s_add_i32 s10, s0, s34
	s_cmpk_gt_i32 s10, 0x87f
	s_waitcnt lgkmcnt(0)
	s_barrier
	s_cbranch_scc1 .LBB0_333
	s_sub_i32 s0, s33, s15
	v_lshlrev_b32_e32 v0, 3, v166
	s_lshl_b32 s11, s0, 3
	s_mul_i32 s0, s34, 0x2100
	v_ashrrev_i32_e32 v38, 3, v166
	v_and_b32_e32 v0, 56, v0
	s_add_i32 s0, s0, 0
	v_and_b32_e32 v36, 31, v166
	v_mul_u32_u24_e32 v3, 0x84, v0
	v_lshlrev_b32_e32 v4, 2, v38
	s_and_b32 s6, s34, 7
	v_lshl_add_u32 v1, v36, 2, s0
	v_add3_u32 v3, s0, v3, v4
	s_mul_i32 s0, s6, 0x48000
	v_ashrrev_i32_e32 v37, 5, v166
	s_movk_i32 s1, 0x84
	s_add_u32 s0, s4, s0
	v_mul_lo_u32 v2, v37, s1
	s_addc_u32 s1, s5, 0
	s_lshl_b32 s4, s6, 9
	s_add_i32 s12, s4, 0
	s_lshl_b32 s4, s33, 6
	s_lshl_b32 s5, s15, 6
	v_add_u32_e32 v1, v1, v2
	v_mov_b32_e32 v21, 0
	s_mul_i32 s13, s6, 0x480000
	s_lshl_b32 s14, s10, 3
	s_sub_i32 s15, s4, s5
	s_movk_i32 s16, 0xaff
	s_movk_i32 s17, 0x5800
	s_mov_b32 s18, 0xb000
	s_mov_b32 s19, 0x16000
	s_mov_b32 s20, 0x21000
	s_mov_b32 s21, 0x2c000
	s_mov_b32 s22, 0x37000
	s_mov_b32 s23, 0x42000
	s_mov_b32 s24, 0x4d000
	s_mov_b32 s25, 0x58000
	s_mov_b32 s26, 0x63000
	s_mov_b32 s27, 0x6e000
	s_mov_b32 s28, 0x79000
	s_mov_b32 s29, 0x84000
	s_mov_b32 s33, 0x8f000
	s_mov_b32 s34, 0x9a000
	s_mov_b32 s35, 0xa5000
	s_mov_b32 s36, 0xb0000
	s_mov_b32 s37, 0xbb000
	s_mov_b32 s38, 0xc6000
	s_mov_b32 s39, 0xd1000
	s_mov_b32 s40, 0xdc000
	s_mov_b32 s41, 0xe7000
	s_mov_b32 s42, 0xf2000
	s_mov_b32 s43, 0xfd000
	s_mov_b32 s44, 0x108000
	s_mov_b32 s45, 0x113000
	s_mov_b32 s46, 0x11e000
	s_mov_b32 s47, 0x129000
	s_mov_b32 s48, 0x134000
	s_mov_b32 s49, 0x13f000
	s_mov_b32 s50, 0x14a000
	s_mov_b32 s51, 0x155000
	s_movk_i32 s52, 0x1600
	s_movk_i32 s53, 0x80
	s_movk_i32 s54, 0xff00
	v_add_u32_e32 v39, 0x8000, v1
	v_add_u32_e32 v40, 0x8400, v1
	v_add_u32_e32 v41, 0x8800, v1
	v_add_u32_e32 v42, 0x8c00, v1
	v_add_u32_e32 v43, 0x9000, v1
	v_add_u32_e32 v44, 0x9400, v1
	v_add_u32_e32 v45, 0x9800, v1
	v_add_u32_e32 v46, 0x9c00, v1
	v_add_u32_e32 v47, 0x8000, v3
	v_lshlrev_b32_e32 v22, 1, v0
	s_branch .LBB0_303
.LBB0_302:
	s_add_i32 s10, s10, s11
	s_add_i32 s14, s14, s15
	s_cmpk_lt_i32 s10, 0x880
	s_cbranch_scc0 .LBB0_333

.LBB0_723:
	s_or_b64 exec, exec, s[0:1]
	s_sub_i32 s0, s41, s19
	s_lshl_b32 s1, s0, 3
	s_add_i32 s0, s40, 0x880
	s_add_i32 s10, s1, s0
	s_cmpk_gt_i32 s10, 0x2234
	s_waitcnt lgkmcnt(0)
	s_barrier
	s_cbranch_scc1 .LBB0_769
	s_sub_i32 s1, s33, s19
	s_lshl_b32 s11, s1, 3
	s_add_u32 s12, s8, 0xa00000
	s_addc_u32 s13, s9, 0
	s_add_u32 s14, s8, 0x3600000
	v_ashrrev_i32_e32 v37, 5, v181
	s_movk_i32 s4, 0x84
	s_addc_u32 s15, s9, 0
	s_mul_i32 s1, s40, 0x2100
	v_mul_lo_u32 v2, v37, s4
	v_lshlrev_b32_e32 v0, 3, v181
	s_and_b32 s4, s0, 7
	s_add_i32 s1, s1, 0
	v_ashrrev_i32_e32 v38, 3, v181
	v_and_b32_e32 v0, 56, v0
	s_mul_i32 s0, s4, 0x48000
	v_and_b32_e32 v36, 31, v181
	v_mul_u32_u24_e32 v3, 0x84, v0
	v_lshlrev_b32_e32 v4, 2, v38
	s_add_u32 s0, s8, s0
	v_lshl_add_u32 v1, v36, 2, s1
	v_add3_u32 v3, s1, v3, v4
	s_addc_u32 s1, s9, 0
	s_lshl_b32 s4, s4, 9
	s_add_i32 s40, s40, 2
	s_add_i32 s16, s4, 0
	s_and_b32 s4, s40, 7
	s_mul_i32 s17, s4, 0x480000
	s_lshl_b32 s4, s33, 6
	s_lshl_b32 s5, s19, 6
	v_add_u32_e32 v1, v1, v2
	v_add_u32_e32 v39, 8, v38
	v_add_u32_e32 v40, 16, v38
	v_add_u32_e32 v41, 24, v38
	v_mov_b32_e32 v21, 0
	s_lshl_b32 s18, s10, 3
	s_sub_i32 s19, s4, s5
	s_movk_i32 s20, 0x6000
	s_mov_b32 s21, 0x8000
	s_mov_b32 s22, 0xa000
	s_mov_b32 s23, 0xc000
	s_mov_b32 s24, 0x10000
	s_mov_b32 s25, 0x12000
	s_mov_b32 s26, 0x14000
	s_mov_b32 s27, 0x16000
	s_mov_b32 s28, 0x18000
	s_mov_b32 s29, 0x1a000
	s_mov_b32 s30, 0x1c000
	s_mov_b32 s31, 0x1e000
	s_mov_b32 s33, 0x20000
	s_mov_b32 s34, 0x22000
	s_mov_b32 s35, 0x24000
	s_mov_b32 s36, 0x26000
	s_mov_b32 s37, 0x28000
	s_mov_b32 s38, 0x2a000
	s_mov_b32 s39, 0x2c000
	s_mov_b32 s40, 0x2e000
	s_mov_b32 s41, 0x30000
	s_mov_b32 s42, 0x32000
	s_mov_b32 s43, 0x34000
	s_mov_b32 s44, 0x36000
	s_mov_b32 s45, 0x38000
	s_mov_b32 s46, 0x3a000
	s_mov_b32 s47, 0x3c000
	s_mov_b32 s48, 0x3e000
	s_movk_i32 s49, 0x400
	s_movk_i32 s50, 0xaff
	s_movk_i32 s51, 0x5800
	s_mov_b32 s52, 0xb000
	s_mov_b32 s53, 0x21000
	s_mov_b32 s54, 0x37000
	s_mov_b32 s55, 0x42000
	s_mov_b32 s56, 0x4d000
	s_mov_b32 s57, 0x58000
	s_mov_b32 s58, 0x63000
	s_mov_b32 s59, 0x6e000
	s_mov_b32 s60, 0x79000
	s_mov_b32 s61, 0x84000
	s_mov_b32 s62, 0x8f000
	s_mov_b32 s63, 0x9a000
	s_mov_b32 s64, 0xa5000
	s_mov_b32 s65, 0xb0000
	s_mov_b32 s66, 0xbb000
	s_mov_b32 s67, 0xc6000
	s_mov_b32 s68, 0xd1000
	s_mov_b32 s69, 0xdc000
	s_mov_b32 s70, 0xe7000
	s_mov_b32 s71, 0xf2000
	s_mov_b32 s72, 0xfd000
	s_mov_b32 s73, 0x108000
	s_mov_b32 s74, 0x113000
	s_mov_b32 s75, 0x11e000
	s_mov_b32 s76, 0x129000
	s_mov_b32 s77, 0x134000
	s_mov_b32 s78, 0x13f000
	s_mov_b32 s79, 0x14a000
	s_mov_b32 s80, 0x155000
	s_movk_i32 s81, 0x1600
	s_movk_i32 s82, 0x80
	s_movk_i32 s83, 0xff00
	v_add_u32_e32 v42, 0x8000, v1
	v_add_u32_e32 v43, 0x8400, v1
	v_add_u32_e32 v44, 0x8800, v1
	v_add_u32_e32 v45, 0x8c00, v1
	v_add_u32_e32 v46, 0x9000, v1
	v_add_u32_e32 v47, 0x9400, v1
	v_add_u32_e32 v48, 0x9800, v1
	v_add_u32_e32 v49, 0x9c00, v1
	v_add_u32_e32 v50, 0x8000, v3
	v_lshlrev_b32_e32 v22, 1, v0
	s_branch .LBB0_726
